# w_in GEMM additionally waits for every down-projection unit (its output reuses the FFN hidden buffer with another row stride)
# speedup vs baseline: 1.0447x; 1.0001x over previous
.LBB0_388:
	s_or_b64 exec, exec, s[4:5]
	s_cmp_eq_u32 s51, 1
	s_mov_b64 s[4:5], -1
	s_waitcnt lgkmcnt(0)
	s_barrier
	s_cmp_lg_u32 s86, 0
	s_cbranch_scc1 .Lhf_done
	s_load_dwordx2 s[6:7], s[66:67], 0x100
	v_mov_b32_e32 v0, 0x2017c
	ds_read_b32 v2, v0
	v_readlane_b32 s0, v255, 0
	s_nop 3
	s_and_b32 s1, s0, 7
	s_lshr_b32 s2, s0, 3
	s_cmp_eq_u32 s51, 1
	s_cbranch_scc1 .Lhf_in
	s_mul_i32 s3, s1, 88
	s_add_i32 s3, s3, s2
	s_mul_i32 s8, s3, 0x5d18
	s_lshr_b32 s8, s8, 22
	s_mul_i32 s14, s8, 0xb0
	s_sub_i32 s14, s3, s14
	s_and_b32 s14, s14, 7
	s_lshl_b32 s8, s8, 3
	s_add_i32 s8, s8, s14
	s_add_i32 s15, s3, 32
	s_mul_i32 s9, s15, 0x5d18
	s_lshr_b32 s9, s9, 22
	s_mul_i32 s14, s9, 0xb0
	s_sub_i32 s14, s15, s14
	s_and_b32 s14, s14, 7
	s_lshl_b32 s9, s9, 3
	s_add_i32 s9, s9, s14
	s_add_i32 s15, s3, 64
	s_cmp_lt_u32 s0, 0xc0
	s_cselect_b32 s15, s15, s3
	s_mul_i32 s10, s15, 0x5d18
	s_lshr_b32 s10, s10, 22
	s_mul_i32 s14, s10, 0xb0
	s_sub_i32 s14, s15, s14
	s_and_b32 s14, s14, 7
	s_lshl_b32 s10, s10, 3
	s_add_i32 s10, s10, s14
	v_mov_b32_e32 v9, 0
	s_branch .Lhf_poll
.Lhf_in:
	s_lshl_b32 s8, s1, 2
	s_and_b32 s2, s2, 3
	s_add_i32 s8, s8, s2
	s_mov_b32 s9, s8
	s_mov_b32 s10, s8
	v_mov_b32_e32 v9, 0x20178
	ds_read_b32 v9, v9
.Lhf_poll:
	s_lshl_b32 s8, s8, 4
	s_lshl_b32 s9, s9, 4
	s_lshl_b32 s10, s10, 4
	s_add_i32 s8, s8, 0x3e00
	s_add_i32 s9, s9, 0x3e00
	s_add_i32 s10, s10, 0x3e00
	v_mov_b32_e32 v3, s8
	v_mov_b32_e32 v4, s9
	v_mov_b32_e32 v5, s10
	v_mbcnt_lo_u32_b32 v10, -1, 0
	v_mbcnt_hi_u32_b32 v10, -1, v10
	v_and_b32_e32 v10, 31, v10
	v_lshlrev_b32_e32 v10, 5, v10
	v_add_u32_e32 v10, 0x3a00, v10
	s_waitcnt lgkmcnt(0)
	s_add_u32 s6, s6, 0xe800000
	s_addc_u32 s7, s7, 0
.Lhf_loop:
	global_load_dword v6, v3, s[6:7] sc1
	global_load_dword v7, v4, s[6:7] sc1
	global_load_dword v8, v5, s[6:7] sc1
	global_load_dword v11, v10, s[6:7] sc1
	s_waitcnt vmcnt(0)
	v_min3_u32 v6, v6, v7, v8
	v_cmp_le_u32_e32 vcc, v2, v6
	s_cbranch_vccz .Lhf_slp
	v_cmp_le_u32_e32 vcc, v9, v11
	s_nop 1
	s_andn2_b64 s[0:1], exec, vcc
	s_cbranch_scc0 .Lhf_rel
.Lhf_slp:
	s_sleep 2
	s_branch .Lhf_loop
